# P4 attention second task (gathered tile): software-pipelined fully unrolled 8-step body, QK MFMAs of step i+1 issued inside softmax of step i, two score buffers, K/V LDS reads with immediate offsets
# speedup vs baseline: 1.0039x; 1.0005x over previous
; DI void attn_task(const Params& P, int bh, int n, int t, int lane, const char* Ks, const char* Vs) {
;     ...
;   bf16x8 qf[4];
;   {
;     const u16* qrow = Qb + ((long)(b * 8192 + lq)) * 512 + h * 64 + 8 * hh;
; #pragma unroll
;     for (int s = 0; s < 4; ++s) qf[s] = *reinterpret_cast<const bf16x8*>(qrow + 16 * s);
;   }
;   float m_run = -1e30f, l_run = 0.f;
;   f32x16 O0, O1;
; #pragma unroll
;   for (int i = 0; i < 16; ++i) { O0[i] = 0.f; O1[i] = 0.f; }
;   const int nkt = own ? (t + 1) : 8;
;   for (int kt = 0; kt < nkt; ++kt) {
.LBB0_778:
	s_andn2_saveexec_b64 s[0:1], s[0:1]
	v_lshl_add_u32 v0, v0, 5, v145
	v_or_b32_e32 v148, v0, v97
	v_mov_b64_e32 v[88:89], 3
	s_or_b64 s[24:25], s[24:25], exec
	s_or_b64 exec, exec, s[0:1]
	v_lshlrev_b32_e32 v0, 10, v74
	v_and_b32_e32 v0, 0xffffe000, v0
	v_add_u32_e32 v90, v148, v0
	v_bfe_u32 v89, v66, 5, 3
	v_ashrrev_i32_e32 v91, 31, v90
	v_cmp_lt_i32_e32 vcc, -9, v75
	v_mov_b32_e32 v147, 0xf149f2ca
	v_mov_b32_e32 v31, 0
	v_mov_b32_e32 v30, 0
	v_mov_b32_e32 v29, 0
	v_mov_b32_e32 v28, 0
	v_mov_b32_e32 v27, 0
	v_mov_b32_e32 v26, 0
	v_mov_b32_e32 v25, 0
	v_mov_b32_e32 v24, 0
	v_mov_b32_e32 v23, 0
	v_mov_b32_e32 v22, 0
	v_mov_b32_e32 v21, 0
	v_mov_b32_e32 v20, 0
	v_mov_b32_e32 v19, 0
	v_mov_b32_e32 v18, 0
	v_mov_b32_e32 v17, 0
	v_mov_b32_e32 v16, 0
	v_mov_b32_e32 v47, 0
	v_mov_b32_e32 v46, 0
	v_mov_b32_e32 v45, 0
	v_mov_b32_e32 v44, 0
	v_mov_b32_e32 v43, 0
	v_mov_b32_e32 v42, 0
	v_mov_b32_e32 v41, 0
	v_mov_b32_e32 v40, 0
	v_mov_b32_e32 v39, 0
	v_mov_b32_e32 v38, 0
	v_mov_b32_e32 v37, 0
	v_mov_b32_e32 v36, 0
	v_mov_b32_e32 v35, 0
	v_mov_b32_e32 v34, 0
	v_mov_b32_e32 v33, 0
	v_mov_b32_e32 v32, 0
	v_mov_b32_e32 v4, 0
	s_and_saveexec_b64 s[48:49], vcc
	s_cbranch_execz .LBB0_795
	v_lshlrev_b64 v[2:3], 10, v[90:91]
	v_lshl_add_u64 v[2:3], s[78:79], 0, v[2:3]
	v_lshlrev_b32_e32 v0, 7, v89
	v_lshl_add_u64 v[2:3], v[2:3], 0, v[0:1]
	v_lshlrev_b32_e32 v0, 1, v84
	v_lshl_add_u64 v[2:3], v[2:3], 0, v[0:1]
	global_load_dwordx4 v[64:67], v[2:3], off
	global_load_dwordx4 v[68:71], v[2:3], off offset:32
	global_load_dwordx4 v[72:75], v[2:3], off offset:64
	global_load_dwordx4 v[76:79], v[2:3], off offset:96
	v_lshl_add_u32 v0, v144, 3, v142
	v_lshlrev_b32_e32 v2, 3, v146
	v_sub_u32_e32 v144, v0, v2
	v_min_u32_e32 v0, 7, v144
	v_mov_b32_e32 v14, v1
	v_mov_b32_e32 v15, v1
	v_lshl_add_u32 v146, v0, 5, 32
	v_mov_b32_e32 v0, v1
	v_mov_b32_e32 v2, v1
	v_mov_b32_e32 v3, v1
	v_mov_b32_e32 v4, v1
	v_mov_b32_e32 v5, v1
	v_mov_b32_e32 v6, v1
	v_mov_b32_e32 v7, v1
	v_mov_b32_e32 v8, v1
	v_mov_b32_e32 v9, v1
	v_mov_b32_e32 v10, v1
	v_mov_b32_e32 v11, v1
	v_mov_b32_e32 v12, v1
	v_mov_b32_e32 v13, v1
	v_mov_b64_e32 v[30:31], v[14:15]
	v_mov_b64_e32 v[46:47], v[14:15]
	v_add_u32_e32 v145, v99, v145
	s_mov_b32 s8, 0
	v_mov_b32_e32 v155, 0
	v_mov_b32_e32 v147, 0xf149f2ca
	s_mov_b64 s[50:51], 0
	v_mov_b32_e32 v149, v139
	v_mov_b32_e32 v150, v138
	v_mov_b32_e32 v151, v137
	v_mov_b32_e32 v152, v136
	v_mov_b32_e32 v153, v134
	v_mov_b32_e32 v154, v85
	v_mov_b64_e32 v[28:29], v[12:13]
	v_mov_b64_e32 v[26:27], v[10:11]
	v_mov_b64_e32 v[24:25], v[8:9]
	v_mov_b64_e32 v[22:23], v[6:7]
	v_mov_b64_e32 v[20:21], v[4:5]
	v_mov_b64_e32 v[18:19], v[2:3]
	v_mov_b64_e32 v[16:17], v[0:1]
	v_mov_b64_e32 v[44:45], v[12:13]
	v_mov_b64_e32 v[42:43], v[10:11]
	v_mov_b64_e32 v[40:41], v[8:9]
	v_mov_b64_e32 v[38:39], v[6:7]
	v_mov_b64_e32 v[36:37], v[4:5]
	v_mov_b64_e32 v[34:35], v[2:3]
	v_mov_b64_e32 v[32:33], v[0:1]
	v_cmp_gt_u32_e32 vcc, 8, v144
	s_cbranch_vccnz .LBB0_783
	s_branch .Lattn_pipe_783

; DI unsigned pack2bf(float a, float b) { const f2_t v = {a, b}; return __builtin_bit_cast(unsigned, __builtin_convertvector(v, bf2_t)); }
; DI void attn_task(const Params& P, int bh, int n, int t, int lane, const char* Ks, const char* Vs) {
;     ...
;   for (int kt = 0; kt < nkt; ++kt) {
;     const int kbase = n * 256 + kt * 32;
;     const int krow = kt * 32 + r;
;     f32x16 S;
; #pragma unroll
;     for (int i = 0; i < 16; ++i) S[i] = 0.f;
; #pragma unroll
;     for (int s = 0; s < 4; ++s) {
;       const bf16x8 kf = *reinterpret_cast<const bf16x8*>(Ks + krow * 128 + (((2 * s + hh) ^ ((krow >> 1) & 7)) * 16));
;       S = __builtin_amdgcn_mfma_f32_32x32x16_bf16(kf, qf[s], S, 0, 0, 0);
;     }
;     const bool diag = own && (kt == t);
;     constexpr float SC2 = 0.125f * 1.4426950408889634f;
;     float mx = -1e30f;
; #pragma unroll
;     for (int i = 0; i < 16; ++i) {
;       if (diag && (kbase + crow(i, hh) > lq)) S[i] = -1e30f;
;       mx = fmaxf(mx, S[i]);
;     }
;     mx = xor32_max(mx);
;     const float m_new = fmaxf(m_run, mx * SC2);
;     const float alpha = __builtin_amdgcn_exp2f(m_run - m_new);
;     float rs = 0.f;
; #pragma unroll
;     for (int i = 0; i < 16; ++i) { float pv = __builtin_amdgcn_exp2f(fmaf(S[i], SC2, -m_new)); S[i] = pv; rs += pv; }
;     rs = xor32_sum(rs);
;     l_run = l_run * alpha + rs; m_run = m_new;
;     if (__ballot(alpha != 1.f)) {
; #pragma unroll
;       for (int i = 0; i < 16; ++i) { O0[i] *= alpha; O1[i] *= alpha; }
;     }
; #pragma unroll
;     for (int s = 0; s < 2; ++s) {
;       const uint4 ppk = make_uint4(pack2bf(S[8 * s], S[8 * s + 1]), pack2bf(S[8 * s + 2], S[8 * s + 3]), pack2bf(S[8 * s + 4], S[8 * s + 5]), pack2bf(S[8 * s + 6], S[8 * s + 7]));
;       const bf16x8 pf = __builtin_bit_cast(bf16x8, ppk);
; #pragma unroll
;       for (int dt = 0; dt < 2; ++dt) {
;         const char* vp = Vs + (dt * 32 + r) * 528 + (kt * 32 + 16 * s + 4 * hh) * 2;
;         const uint2 lo = *reinterpret_cast<const uint2*>(vp), hi = *reinterpret_cast<const uint2*>(vp + 16);
;         const uint4 vv = make_uint4(lo.x, lo.y, hi.x, hi.y);
;         if (dt == 0) O0 = __builtin_amdgcn_mfma_f32_32x32x16_bf16(__builtin_bit_cast(bf16x8, vv), pf, O0, 0, 0, 0);
;         else O1 = __builtin_amdgcn_mfma_f32_32x32x16_bf16(__builtin_bit_cast(bf16x8, vv), pf, O1, 0, 0, 0);
;       }
;     }
.Lattn_pipe_783:
	v_add_u32_e32 v248, v152, v197
	v_add_u32_e32 v249, v151, v197
	v_add_u32_e32 v250, v150, v197
	v_add_u32_e32 v251, v149, v197
	v_add_u32_e32 v210, v153, v197
	v_add_u32_e32 v211, v154, v197
	ds_read_b128 v[176:179], v248 offset:0
	ds_read_b128 v[180:183], v249 offset:0
	ds_read_b128 v[184:187], v250 offset:0
	ds_read_b128 v[200:203], v251 offset:0
	s_waitcnt vmcnt(0) lgkmcnt(0)
	v_mfma_f32_32x32x16_bf16 v[48:63], v[176:179], v[64:67], 0
	v_mfma_f32_32x32x16_bf16 v[48:63], v[180:183], v[68:71], v[48:63]
	v_mfma_f32_32x32x16_bf16 v[48:63], v[184:187], v[72:75], v[48:63]
	v_mfma_f32_32x32x16_bf16 v[48:63], v[200:203], v[76:79], v[48:63]
	ds_read_b128 v[176:179], v248 offset:4096
	ds_read_b128 v[180:183], v249 offset:4096
	ds_read_b128 v[184:187], v250 offset:4096
	ds_read_b128 v[200:203], v251 offset:4096
	s_nop 7
	s_waitcnt lgkmcnt(0)
	v_mfma_f32_32x32x16_bf16 v[232:247], v[176:179], v[64:67], 0
	ds_read2_b64 v[216:219], v210 offset0:0 offset1:2
	ds_read2_b64 v[220:223], v211 offset0:0 offset1:2
	ds_read2_b64 v[224:227], v210 offset0:4 offset1:6
	ds_read2_b64 v[228:231], v211 offset0:4 offset1:6
	v_max3_f32 v4, v48, s22, v49
	v_max3_f32 v4, v4, v50, v51
	v_max3_f32 v4, v4, v52, v53
	v_max3_f32 v4, v4, v54, v55
	v_max3_f32 v4, v4, v56, v57
	v_max3_f32 v4, v4, v58, v59
	v_max3_f32 v4, v4, v60, v61
	v_max3_f32 v4, v4, v62, v63
	v_mfma_f32_32x32x16_bf16 v[232:247], v[180:183], v[68:71], v[232:247]
	v_mov_b32_e32 v5, v4
	s_nop 1
	v_permlane32_swap_b32_e32 v4, v5
	v_max_f32_e32 v4, v4, v5
	v_mul_f32_e32 v4, 0x3e38aa3b, v4
	v_max_f32_e32 v6, v147, v4
	v_sub_f32_e32 v0, v147, v6
	v_pk_fma_f32 v[48:49], v[48:49], s[22:23], v[6:7] op_sel:[0,1,0] op_sel_hi:[1,1,0] neg_lo:[0,0,1] neg_hi:[0,0,1]
	v_pk_fma_f32 v[50:51], v[50:51], s[22:23], v[6:7] op_sel:[0,1,0] op_sel_hi:[1,1,0] neg_lo:[0,0,1] neg_hi:[0,0,1]
	v_pk_fma_f32 v[52:53], v[52:53], s[22:23], v[6:7] op_sel:[0,1,0] op_sel_hi:[1,1,0] neg_lo:[0,0,1] neg_hi:[0,0,1]
	v_pk_fma_f32 v[54:55], v[54:55], s[22:23], v[6:7] op_sel:[0,1,0] op_sel_hi:[1,1,0] neg_lo:[0,0,1] neg_hi:[0,0,1]
	v_pk_fma_f32 v[56:57], v[56:57], s[22:23], v[6:7] op_sel:[0,1,0] op_sel_hi:[1,1,0] neg_lo:[0,0,1] neg_hi:[0,0,1]
	v_pk_fma_f32 v[58:59], v[58:59], s[22:23], v[6:7] op_sel:[0,1,0] op_sel_hi:[1,1,0] neg_lo:[0,0,1] neg_hi:[0,0,1]
	v_pk_fma_f32 v[60:61], v[60:61], s[22:23], v[6:7] op_sel:[0,1,0] op_sel_hi:[1,1,0] neg_lo:[0,0,1] neg_hi:[0,0,1]
	v_pk_fma_f32 v[62:63], v[62:63], s[22:23], v[6:7] op_sel:[0,1,0] op_sel_hi:[1,1,0] neg_lo:[0,0,1] neg_hi:[0,0,1]
	v_mfma_f32_32x32x16_bf16 v[232:247], v[184:187], v[72:75], v[232:247]
	v_exp_f32_e32 v0, v0
	v_exp_f32_e32 v48, v48
	v_exp_f32_e32 v49, v49
	v_exp_f32_e32 v50, v50
	v_exp_f32_e32 v51, v51
	v_exp_f32_e32 v52, v52
	v_exp_f32_e32 v53, v53
	v_exp_f32_e32 v54, v54
	v_mfma_f32_32x32x16_bf16 v[232:247], v[200:203], v[76:79], v[232:247]
	ds_read_b128 v[176:179], v248 offset:8192
	ds_read_b128 v[180:183], v249 offset:8192
	ds_read_b128 v[184:187], v250 offset:8192
	ds_read_b128 v[200:203], v251 offset:8192
	v_exp_f32_e32 v55, v55
	v_exp_f32_e32 v56, v56
	v_exp_f32_e32 v57, v57
	v_exp_f32_e32 v58, v58
	v_exp_f32_e32 v59, v59
	v_exp_f32_e32 v60, v60
	v_exp_f32_e32 v61, v61
	v_exp_f32_e32 v62, v62
	v_exp_f32_e32 v63, v63
	v_mov_b32_e32 v147, v6
	v_pk_add_f32 v[2:3], v[48:49], v[50:51]
	v_pk_add_f32 v[8:9], v[52:53], v[54:55]
	v_pk_add_f32 v[12:13], v[56:57], v[58:59]
	v_pk_add_f32 v[14:15], v[60:61], v[62:63]
	v_pk_add_f32 v[2:3], v[2:3], v[8:9]
	v_pk_add_f32 v[12:13], v[12:13], v[14:15]
	v_pk_add_f32 v[2:3], v[2:3], v[12:13]
	v_add_f32_e32 v10, v2, v3
	v_mov_b32_e32 v11, v10
	s_nop 1
	v_permlane32_swap_b32_e32 v10, v11
	v_cmp_neq_f32_e32 vcc, 1.0, v0
	s_cbranch_vccz .Lattn_pkeep_0
	v_pk_mul_f32 v[30:31], v[30:31], v[0:1] op_sel_hi:[1,0]
	v_pk_mul_f32 v[28:29], v[28:29], v[0:1] op_sel_hi:[1,0]
	v_pk_mul_f32 v[26:27], v[26:27], v[0:1] op_sel_hi:[1,0]
	v_pk_mul_f32 v[24:25], v[24:25], v[0:1] op_sel_hi:[1,0]
	v_pk_mul_f32 v[22:23], v[22:23], v[0:1] op_sel_hi:[1,0]
	v_pk_mul_f32 v[20:21], v[20:21], v[0:1] op_sel_hi:[1,0]
	v_pk_mul_f32 v[18:19], v[18:19], v[0:1] op_sel_hi:[1,0]
	v_pk_mul_f32 v[16:17], v[16:17], v[0:1] op_sel_hi:[1,0]
	v_pk_mul_f32 v[46:47], v[46:47], v[0:1] op_sel_hi:[1,0]
	v_pk_mul_f32 v[44:45], v[44:45], v[0:1] op_sel_hi:[1,0]
	v_pk_mul_f32 v[42:43], v[42:43], v[0:1] op_sel_hi:[1,0]
	v_pk_mul_f32 v[40:41], v[40:41], v[0:1] op_sel_hi:[1,0]
	v_pk_mul_f32 v[38:39], v[38:39], v[0:1] op_sel_hi:[1,0]
	v_pk_mul_f32 v[36:37], v[36:37], v[0:1] op_sel_hi:[1,0]
	v_pk_mul_f32 v[34:35], v[34:35], v[0:1] op_sel_hi:[1,0]
	v_pk_mul_f32 v[32:33], v[32:33], v[0:1] op_sel_hi:[1,0]
; DI unsigned pack2bf(float a, float b) { const f2_t v = {a, b}; return __builtin_bit_cast(unsigned, __builtin_convertvector(v, bf2_t)); }
; DI float xor32_max(float v) { const auto r = __builtin_amdgcn_permlane32_swap(__float_as_uint(v), __float_as_uint(v), false, false); return fmaxf(__uint_as_float(r[0]), __uint_as_float(r[1])); }
; DI void attn_task(const Params& P, int bh, int n, int t, int lane, const char* Ks, const char* Vs) {
;     ...
;     for (int s = 0; s < 4; ++s) {
;       const bf16x8 kf = *reinterpret_cast<const bf16x8*>(Ks + krow * 128 + (((2 * s + hh) ^ ((krow >> 1) & 7)) * 16));
;       S = __builtin_amdgcn_mfma_f32_32x32x16_bf16(kf, qf[s], S, 0, 0, 0);
;     }
;     const bool diag = own && (kt == t);
;     constexpr float SC2 = 0.125f * 1.4426950408889634f;
;     float mx = -1e30f;
; #pragma unroll
;     for (int i = 0; i < 16; ++i) {
;       if (diag && (kbase + crow(i, hh) > lq)) S[i] = -1e30f;
;       mx = fmaxf(mx, S[i]);
;     }
;     mx = xor32_max(mx);
;     const float m_new = fmaxf(m_run, mx * SC2);
;     const float alpha = __builtin_amdgcn_exp2f(m_run - m_new);
;     float rs = 0.f;
; #pragma unroll
;     for (int i = 0; i < 16; ++i) { float pv = __builtin_amdgcn_exp2f(fmaf(S[i], SC2, -m_new)); S[i] = pv; rs += pv; }
;     rs = xor32_sum(rs);
;     l_run = l_run * alpha + rs; m_run = m_new;
;     if (__ballot(alpha != 1.f)) {
; #pragma unroll
;       for (int i = 0; i < 16; ++i) { O0[i] *= alpha; O1[i] *= alpha; }
;     }
; #pragma unroll
;     for (int s = 0; s < 2; ++s) {
;       const uint4 ppk = make_uint4(pack2bf(S[8 * s], S[8 * s + 1]), pack2bf(S[8 * s + 2], S[8 * s + 3]), pack2bf(S[8 * s + 4], S[8 * s + 5]), pack2bf(S[8 * s + 6], S[8 * s + 7]));
;       const bf16x8 pf = __builtin_bit_cast(bf16x8, ppk);
; #pragma unroll
;       for (int dt = 0; dt < 2; ++dt) {
;         const char* vp = Vs + (dt * 32 + r) * 528 + (kt * 32 + 16 * s + 4 * hh) * 2;
;         const uint2 lo = *reinterpret_cast<const uint2*>(vp), hi = *reinterpret_cast<const uint2*>(vp + 16);
;         const uint4 vv = make_uint4(lo.x, lo.y, hi.x, hi.y);
;         if (dt == 0) O0 = __builtin_amdgcn_mfma_f32_32x32x16_bf16(__builtin_bit_cast(bf16x8, vv), pf, O0, 0, 0, 0);
;         else O1 = __builtin_amdgcn_mfma_f32_32x32x16_bf16(__builtin_bit_cast(bf16x8, vv), pf, O1, 0, 0, 0);
;       }
;     }
.Lattn_pkeep_0:
	v_add_f32_e32 v4, v10, v11
	v_fmac_f32_e32 v4, v155, v0
	v_cvt_pk_bf16_f32 v8, v48, v49
	v_cvt_pk_bf16_f32 v9, v50, v51
	v_cvt_pk_bf16_f32 v10, v52, v53
	v_cvt_pk_bf16_f32 v11, v54, v55
	v_cvt_pk_bf16_f32 v12, v56, v57
	v_cvt_pk_bf16_f32 v13, v58, v59
	v_cvt_pk_bf16_f32 v14, v60, v61
	v_cvt_pk_bf16_f32 v15, v62, v63
	v_mov_b32_e32 v155, v4
	s_waitcnt lgkmcnt(0)
	v_mfma_f32_32x32x16_bf16 v[16:31], v[216:219], v[8:11], v[16:31]
	v_mfma_f32_32x32x16_bf16 v[32:47], v[220:223], v[8:11], v[32:47]
	v_mfma_f32_32x32x16_bf16 v[16:31], v[224:227], v[12:15], v[16:31]
	v_mfma_f32_32x32x16_bf16 v[32:47], v[228:231], v[12:15], v[32:47]
	s_waitcnt lgkmcnt(0)
	v_mfma_f32_32x32x16_bf16 v[48:63], v[176:179], v[64:67], 0
	ds_read2_b64 v[216:219], v210 offset0:8 offset1:10
	ds_read2_b64 v[220:223], v211 offset0:8 offset1:10
	ds_read2_b64 v[224:227], v210 offset0:12 offset1:14
	ds_read2_b64 v[228:231], v211 offset0:12 offset1:14
	v_max3_f32 v4, v232, s22, v233
	v_max3_f32 v4, v4, v234, v235
	v_max3_f32 v4, v4, v236, v237
	v_max3_f32 v4, v4, v238, v239
	v_max3_f32 v4, v4, v240, v241
	v_max3_f32 v4, v4, v242, v243
	v_max3_f32 v4, v4, v244, v245
	v_max3_f32 v4, v4, v246, v247
	v_mfma_f32_32x32x16_bf16 v[48:63], v[180:183], v[68:71], v[48:63]
	v_mov_b32_e32 v5, v4
	s_nop 1
	v_permlane32_swap_b32_e32 v4, v5
	v_max_f32_e32 v4, v4, v5
	v_mul_f32_e32 v4, 0x3e38aa3b, v4
	v_max_f32_e32 v6, v147, v4
	v_sub_f32_e32 v0, v147, v6
	v_pk_fma_f32 v[232:233], v[232:233], s[22:23], v[6:7] op_sel:[0,1,0] op_sel_hi:[1,1,0] neg_lo:[0,0,1] neg_hi:[0,0,1]
	v_pk_fma_f32 v[234:235], v[234:235], s[22:23], v[6:7] op_sel:[0,1,0] op_sel_hi:[1,1,0] neg_lo:[0,0,1] neg_hi:[0,0,1]
	v_pk_fma_f32 v[236:237], v[236:237], s[22:23], v[6:7] op_sel:[0,1,0] op_sel_hi:[1,1,0] neg_lo:[0,0,1] neg_hi:[0,0,1]
	v_pk_fma_f32 v[238:239], v[238:239], s[22:23], v[6:7] op_sel:[0,1,0] op_sel_hi:[1,1,0] neg_lo:[0,0,1] neg_hi:[0,0,1]
	v_pk_fma_f32 v[240:241], v[240:241], s[22:23], v[6:7] op_sel:[0,1,0] op_sel_hi:[1,1,0] neg_lo:[0,0,1] neg_hi:[0,0,1]
	v_pk_fma_f32 v[242:243], v[242:243], s[22:23], v[6:7] op_sel:[0,1,0] op_sel_hi:[1,1,0] neg_lo:[0,0,1] neg_hi:[0,0,1]
	v_pk_fma_f32 v[244:245], v[244:245], s[22:23], v[6:7] op_sel:[0,1,0] op_sel_hi:[1,1,0] neg_lo:[0,0,1] neg_hi:[0,0,1]
	v_pk_fma_f32 v[246:247], v[246:247], s[22:23], v[6:7] op_sel:[0,1,0] op_sel_hi:[1,1,0] neg_lo:[0,0,1] neg_hi:[0,0,1]
	v_mfma_f32_32x32x16_bf16 v[48:63], v[184:187], v[72:75], v[48:63]
	v_exp_f32_e32 v0, v0
	v_exp_f32_e32 v232, v232
	v_exp_f32_e32 v233, v233
	v_exp_f32_e32 v234, v234
	v_exp_f32_e32 v235, v235
	v_exp_f32_e32 v236, v236
	v_exp_f32_e32 v237, v237
	v_exp_f32_e32 v238, v238
	v_mfma_f32_32x32x16_bf16 v[48:63], v[200:203], v[76:79], v[48:63]
	ds_read_b128 v[176:179], v248 offset:12288
	ds_read_b128 v[180:183], v249 offset:12288
	ds_read_b128 v[184:187], v250 offset:12288
	ds_read_b128 v[200:203], v251 offset:12288
	v_exp_f32_e32 v239, v239
	v_exp_f32_e32 v240, v240
	v_exp_f32_e32 v241, v241
	v_exp_f32_e32 v242, v242
	v_exp_f32_e32 v243, v243
	v_exp_f32_e32 v244, v244
	v_exp_f32_e32 v245, v245
	v_exp_f32_e32 v246, v246
	v_exp_f32_e32 v247, v247
	v_mov_b32_e32 v147, v6
	v_pk_add_f32 v[2:3], v[232:233], v[234:235]
	v_pk_add_f32 v[8:9], v[236:237], v[238:239]
	v_pk_add_f32 v[12:13], v[240:241], v[242:243]
	v_pk_add_f32 v[14:15], v[244:245], v[246:247]
	v_pk_add_f32 v[2:3], v[2:3], v[8:9]
	v_pk_add_f32 v[12:13], v[12:13], v[14:15]
	v_pk_add_f32 v[2:3], v[2:3], v[12:13]
	v_add_f32_e32 v10, v2, v3
	v_mov_b32_e32 v11, v10
	s_nop 1
	v_permlane32_swap_b32_e32 v10, v11
	v_cmp_neq_f32_e32 vcc, 1.0, v0
	s_cbranch_vccz .Lattn_pkeep_1
	v_pk_mul_f32 v[30:31], v[30:31], v[0:1] op_sel_hi:[1,0]
	v_pk_mul_f32 v[28:29], v[28:29], v[0:1] op_sel_hi:[1,0]
	v_pk_mul_f32 v[26:27], v[26:27], v[0:1] op_sel_hi:[1,0]
	v_pk_mul_f32 v[24:25], v[24:25], v[0:1] op_sel_hi:[1,0]
	v_pk_mul_f32 v[22:23], v[22:23], v[0:1] op_sel_hi:[1,0]
	v_pk_mul_f32 v[20:21], v[20:21], v[0:1] op_sel_hi:[1,0]
	v_pk_mul_f32 v[18:19], v[18:19], v[0:1] op_sel_hi:[1,0]
	v_pk_mul_f32 v[16:17], v[16:17], v[0:1] op_sel_hi:[1,0]
	v_pk_mul_f32 v[46:47], v[46:47], v[0:1] op_sel_hi:[1,0]
	v_pk_mul_f32 v[44:45], v[44:45], v[0:1] op_sel_hi:[1,0]
	v_pk_mul_f32 v[42:43], v[42:43], v[0:1] op_sel_hi:[1,0]
	v_pk_mul_f32 v[40:41], v[40:41], v[0:1] op_sel_hi:[1,0]
	v_pk_mul_f32 v[38:39], v[38:39], v[0:1] op_sel_hi:[1,0]
	v_pk_mul_f32 v[36:37], v[36:37], v[0:1] op_sel_hi:[1,0]
	v_pk_mul_f32 v[34:35], v[34:35], v[0:1] op_sel_hi:[1,0]
	v_pk_mul_f32 v[32:33], v[32:33], v[0:1] op_sel_hi:[1,0]
; DI unsigned pack2bf(float a, float b) { const f2_t v = {a, b}; return __builtin_bit_cast(unsigned, __builtin_convertvector(v, bf2_t)); }
; DI float xor32_max(float v) { const auto r = __builtin_amdgcn_permlane32_swap(__float_as_uint(v), __float_as_uint(v), false, false); return fmaxf(__uint_as_float(r[0]), __uint_as_float(r[1])); }
; DI void attn_task(const Params& P, int bh, int n, int t, int lane, const char* Ks, const char* Vs) {
;     ...
;     for (int s = 0; s < 4; ++s) {
;       const bf16x8 kf = *reinterpret_cast<const bf16x8*>(Ks + krow * 128 + (((2 * s + hh) ^ ((krow >> 1) & 7)) * 16));
;       S = __builtin_amdgcn_mfma_f32_32x32x16_bf16(kf, qf[s], S, 0, 0, 0);
;     }
;     const bool diag = own && (kt == t);
;     constexpr float SC2 = 0.125f * 1.4426950408889634f;
;     float mx = -1e30f;
; #pragma unroll
;     for (int i = 0; i < 16; ++i) {
;       if (diag && (kbase + crow(i, hh) > lq)) S[i] = -1e30f;
;       mx = fmaxf(mx, S[i]);
;     }
;     mx = xor32_max(mx);
;     const float m_new = fmaxf(m_run, mx * SC2);
;     const float alpha = __builtin_amdgcn_exp2f(m_run - m_new);
;     float rs = 0.f;
; #pragma unroll
;     for (int i = 0; i < 16; ++i) { float pv = __builtin_amdgcn_exp2f(fmaf(S[i], SC2, -m_new)); S[i] = pv; rs += pv; }
;     rs = xor32_sum(rs);
;     l_run = l_run * alpha + rs; m_run = m_new;
;     if (__ballot(alpha != 1.f)) {
; #pragma unroll
;       for (int i = 0; i < 16; ++i) { O0[i] *= alpha; O1[i] *= alpha; }
;     }
; #pragma unroll
;     for (int s = 0; s < 2; ++s) {
;       const uint4 ppk = make_uint4(pack2bf(S[8 * s], S[8 * s + 1]), pack2bf(S[8 * s + 2], S[8 * s + 3]), pack2bf(S[8 * s + 4], S[8 * s + 5]), pack2bf(S[8 * s + 6], S[8 * s + 7]));
;       const bf16x8 pf = __builtin_bit_cast(bf16x8, ppk);
; #pragma unroll
;       for (int dt = 0; dt < 2; ++dt) {
;         const char* vp = Vs + (dt * 32 + r) * 528 + (kt * 32 + 16 * s + 4 * hh) * 2;
;         const uint2 lo = *reinterpret_cast<const uint2*>(vp), hi = *reinterpret_cast<const uint2*>(vp + 16);
;         const uint4 vv = make_uint4(lo.x, lo.y, hi.x, hi.y);
;         if (dt == 0) O0 = __builtin_amdgcn_mfma_f32_32x32x16_bf16(__builtin_bit_cast(bf16x8, vv), pf, O0, 0, 0, 0);
;         else O1 = __builtin_amdgcn_mfma_f32_32x32x16_bf16(__builtin_bit_cast(bf16x8, vv), pf, O1, 0, 0, 0);
;       }
;     }
.Lattn_pkeep_1:
	v_add_f32_e32 v4, v10, v11
	v_fmac_f32_e32 v4, v155, v0
	v_cvt_pk_bf16_f32 v8, v232, v233
	v_cvt_pk_bf16_f32 v9, v234, v235
	v_cvt_pk_bf16_f32 v10, v236, v237
	v_cvt_pk_bf16_f32 v11, v238, v239
	v_cvt_pk_bf16_f32 v12, v240, v241
	v_cvt_pk_bf16_f32 v13, v242, v243
	v_cvt_pk_bf16_f32 v14, v244, v245
	v_cvt_pk_bf16_f32 v15, v246, v247
	v_mov_b32_e32 v155, v4
	s_waitcnt lgkmcnt(0)
	v_mfma_f32_32x32x16_bf16 v[16:31], v[216:219], v[8:11], v[16:31]
	v_mfma_f32_32x32x16_bf16 v[32:47], v[220:223], v[8:11], v[32:47]
	v_mfma_f32_32x32x16_bf16 v[16:31], v[224:227], v[12:15], v[16:31]
	v_mfma_f32_32x32x16_bf16 v[32:47], v[228:231], v[12:15], v[32:47]
	s_waitcnt lgkmcnt(0)
	v_mfma_f32_32x32x16_bf16 v[232:247], v[176:179], v[64:67], 0
	ds_read2_b64 v[216:219], v210 offset0:16 offset1:18
	ds_read2_b64 v[220:223], v211 offset0:16 offset1:18
	ds_read2_b64 v[224:227], v210 offset0:20 offset1:22
	ds_read2_b64 v[228:231], v211 offset0:20 offset1:22
	v_max3_f32 v4, v48, s22, v49
	v_max3_f32 v4, v4, v50, v51
	v_max3_f32 v4, v4, v52, v53
	v_max3_f32 v4, v4, v54, v55
	v_max3_f32 v4, v4, v56, v57
	v_max3_f32 v4, v4, v58, v59
	v_max3_f32 v4, v4, v60, v61
	v_max3_f32 v4, v4, v62, v63
	v_mfma_f32_32x32x16_bf16 v[232:247], v[180:183], v[68:71], v[232:247]
	v_mov_b32_e32 v5, v4
	s_nop 1
	v_permlane32_swap_b32_e32 v4, v5
	v_max_f32_e32 v4, v4, v5
	v_mul_f32_e32 v4, 0x3e38aa3b, v4
	v_max_f32_e32 v6, v147, v4
	v_sub_f32_e32 v0, v147, v6
	v_pk_fma_f32 v[48:49], v[48:49], s[22:23], v[6:7] op_sel:[0,1,0] op_sel_hi:[1,1,0] neg_lo:[0,0,1] neg_hi:[0,0,1]
	v_pk_fma_f32 v[50:51], v[50:51], s[22:23], v[6:7] op_sel:[0,1,0] op_sel_hi:[1,1,0] neg_lo:[0,0,1] neg_hi:[0,0,1]
	v_pk_fma_f32 v[52:53], v[52:53], s[22:23], v[6:7] op_sel:[0,1,0] op_sel_hi:[1,1,0] neg_lo:[0,0,1] neg_hi:[0,0,1]
	v_pk_fma_f32 v[54:55], v[54:55], s[22:23], v[6:7] op_sel:[0,1,0] op_sel_hi:[1,1,0] neg_lo:[0,0,1] neg_hi:[0,0,1]
	v_pk_fma_f32 v[56:57], v[56:57], s[22:23], v[6:7] op_sel:[0,1,0] op_sel_hi:[1,1,0] neg_lo:[0,0,1] neg_hi:[0,0,1]
	v_pk_fma_f32 v[58:59], v[58:59], s[22:23], v[6:7] op_sel:[0,1,0] op_sel_hi:[1,1,0] neg_lo:[0,0,1] neg_hi:[0,0,1]
	v_pk_fma_f32 v[60:61], v[60:61], s[22:23], v[6:7] op_sel:[0,1,0] op_sel_hi:[1,1,0] neg_lo:[0,0,1] neg_hi:[0,0,1]
	v_pk_fma_f32 v[62:63], v[62:63], s[22:23], v[6:7] op_sel:[0,1,0] op_sel_hi:[1,1,0] neg_lo:[0,0,1] neg_hi:[0,0,1]
	v_mfma_f32_32x32x16_bf16 v[232:247], v[184:187], v[72:75], v[232:247]
	v_exp_f32_e32 v0, v0
	v_exp_f32_e32 v48, v48
	v_exp_f32_e32 v49, v49
	v_exp_f32_e32 v50, v50
	v_exp_f32_e32 v51, v51
	v_exp_f32_e32 v52, v52
	v_exp_f32_e32 v53, v53
	v_exp_f32_e32 v54, v54
	v_mfma_f32_32x32x16_bf16 v[232:247], v[200:203], v[76:79], v[232:247]
	ds_read_b128 v[176:179], v248 offset:16384
	ds_read_b128 v[180:183], v249 offset:16384
	ds_read_b128 v[184:187], v250 offset:16384
	ds_read_b128 v[200:203], v251 offset:16384
	v_exp_f32_e32 v55, v55
	v_exp_f32_e32 v56, v56
	v_exp_f32_e32 v57, v57
	v_exp_f32_e32 v58, v58
	v_exp_f32_e32 v59, v59
	v_exp_f32_e32 v60, v60
	v_exp_f32_e32 v61, v61
	v_exp_f32_e32 v62, v62
	v_exp_f32_e32 v63, v63
	v_mov_b32_e32 v147, v6
	v_pk_add_f32 v[2:3], v[48:49], v[50:51]
	v_pk_add_f32 v[8:9], v[52:53], v[54:55]
	v_pk_add_f32 v[12:13], v[56:57], v[58:59]
	v_pk_add_f32 v[14:15], v[60:61], v[62:63]
	v_pk_add_f32 v[2:3], v[2:3], v[8:9]
	v_pk_add_f32 v[12:13], v[12:13], v[14:15]
	v_pk_add_f32 v[2:3], v[2:3], v[12:13]
	v_add_f32_e32 v10, v2, v3
	v_mov_b32_e32 v11, v10
	s_nop 1
	v_permlane32_swap_b32_e32 v10, v11
	v_cmp_neq_f32_e32 vcc, 1.0, v0
	s_cbranch_vccz .Lattn_pkeep_2
	v_pk_mul_f32 v[30:31], v[30:31], v[0:1] op_sel_hi:[1,0]
	v_pk_mul_f32 v[28:29], v[28:29], v[0:1] op_sel_hi:[1,0]
	v_pk_mul_f32 v[26:27], v[26:27], v[0:1] op_sel_hi:[1,0]
	v_pk_mul_f32 v[24:25], v[24:25], v[0:1] op_sel_hi:[1,0]
	v_pk_mul_f32 v[22:23], v[22:23], v[0:1] op_sel_hi:[1,0]
	v_pk_mul_f32 v[20:21], v[20:21], v[0:1] op_sel_hi:[1,0]
	v_pk_mul_f32 v[18:19], v[18:19], v[0:1] op_sel_hi:[1,0]
	v_pk_mul_f32 v[16:17], v[16:17], v[0:1] op_sel_hi:[1,0]
	v_pk_mul_f32 v[46:47], v[46:47], v[0:1] op_sel_hi:[1,0]
	v_pk_mul_f32 v[44:45], v[44:45], v[0:1] op_sel_hi:[1,0]
	v_pk_mul_f32 v[42:43], v[42:43], v[0:1] op_sel_hi:[1,0]
	v_pk_mul_f32 v[40:41], v[40:41], v[0:1] op_sel_hi:[1,0]
	v_pk_mul_f32 v[38:39], v[38:39], v[0:1] op_sel_hi:[1,0]
	v_pk_mul_f32 v[36:37], v[36:37], v[0:1] op_sel_hi:[1,0]
	v_pk_mul_f32 v[34:35], v[34:35], v[0:1] op_sel_hi:[1,0]
	v_pk_mul_f32 v[32:33], v[32:33], v[0:1] op_sel_hi:[1,0]
; DI unsigned pack2bf(float a, float b) { const f2_t v = {a, b}; return __builtin_bit_cast(unsigned, __builtin_convertvector(v, bf2_t)); }
; DI float xor32_max(float v) { const auto r = __builtin_amdgcn_permlane32_swap(__float_as_uint(v), __float_as_uint(v), false, false); return fmaxf(__uint_as_float(r[0]), __uint_as_float(r[1])); }
; DI void attn_task(const Params& P, int bh, int n, int t, int lane, const char* Ks, const char* Vs) {
;     ...
;     for (int s = 0; s < 4; ++s) {
;       const bf16x8 kf = *reinterpret_cast<const bf16x8*>(Ks + krow * 128 + (((2 * s + hh) ^ ((krow >> 1) & 7)) * 16));
;       S = __builtin_amdgcn_mfma_f32_32x32x16_bf16(kf, qf[s], S, 0, 0, 0);
;     }
;     const bool diag = own && (kt == t);
;     constexpr float SC2 = 0.125f * 1.4426950408889634f;
;     float mx = -1e30f;
; #pragma unroll
;     for (int i = 0; i < 16; ++i) {
;       if (diag && (kbase + crow(i, hh) > lq)) S[i] = -1e30f;
;       mx = fmaxf(mx, S[i]);
;     }
;     mx = xor32_max(mx);
;     const float m_new = fmaxf(m_run, mx * SC2);
;     const float alpha = __builtin_amdgcn_exp2f(m_run - m_new);
;     float rs = 0.f;
; #pragma unroll
;     for (int i = 0; i < 16; ++i) { float pv = __builtin_amdgcn_exp2f(fmaf(S[i], SC2, -m_new)); S[i] = pv; rs += pv; }
;     rs = xor32_sum(rs);
;     l_run = l_run * alpha + rs; m_run = m_new;
;     if (__ballot(alpha != 1.f)) {
; #pragma unroll
;       for (int i = 0; i < 16; ++i) { O0[i] *= alpha; O1[i] *= alpha; }
;     }
; #pragma unroll
;     for (int s = 0; s < 2; ++s) {
;       const uint4 ppk = make_uint4(pack2bf(S[8 * s], S[8 * s + 1]), pack2bf(S[8 * s + 2], S[8 * s + 3]), pack2bf(S[8 * s + 4], S[8 * s + 5]), pack2bf(S[8 * s + 6], S[8 * s + 7]));
;       const bf16x8 pf = __builtin_bit_cast(bf16x8, ppk);
; #pragma unroll
;       for (int dt = 0; dt < 2; ++dt) {
;         const char* vp = Vs + (dt * 32 + r) * 528 + (kt * 32 + 16 * s + 4 * hh) * 2;
;         const uint2 lo = *reinterpret_cast<const uint2*>(vp), hi = *reinterpret_cast<const uint2*>(vp + 16);
;         const uint4 vv = make_uint4(lo.x, lo.y, hi.x, hi.y);
;         if (dt == 0) O0 = __builtin_amdgcn_mfma_f32_32x32x16_bf16(__builtin_bit_cast(bf16x8, vv), pf, O0, 0, 0, 0);
;         else O1 = __builtin_amdgcn_mfma_f32_32x32x16_bf16(__builtin_bit_cast(bf16x8, vv), pf, O1, 0, 0, 0);
;       }
;     }
.Lattn_pkeep_2:
	v_add_f32_e32 v4, v10, v11
	v_fmac_f32_e32 v4, v155, v0
	v_cvt_pk_bf16_f32 v8, v48, v49
	v_cvt_pk_bf16_f32 v9, v50, v51
	v_cvt_pk_bf16_f32 v10, v52, v53
	v_cvt_pk_bf16_f32 v11, v54, v55
	v_cvt_pk_bf16_f32 v12, v56, v57
	v_cvt_pk_bf16_f32 v13, v58, v59
	v_cvt_pk_bf16_f32 v14, v60, v61
	v_cvt_pk_bf16_f32 v15, v62, v63
	v_mov_b32_e32 v155, v4
	s_waitcnt lgkmcnt(0)
	v_mfma_f32_32x32x16_bf16 v[16:31], v[216:219], v[8:11], v[16:31]
	v_mfma_f32_32x32x16_bf16 v[32:47], v[220:223], v[8:11], v[32:47]
	v_mfma_f32_32x32x16_bf16 v[16:31], v[224:227], v[12:15], v[16:31]
	v_mfma_f32_32x32x16_bf16 v[32:47], v[228:231], v[12:15], v[32:47]
	s_waitcnt lgkmcnt(0)
	v_mfma_f32_32x32x16_bf16 v[48:63], v[176:179], v[64:67], 0
	ds_read2_b64 v[216:219], v210 offset0:24 offset1:26
	ds_read2_b64 v[220:223], v211 offset0:24 offset1:26
	ds_read2_b64 v[224:227], v210 offset0:28 offset1:30
	ds_read2_b64 v[228:231], v211 offset0:28 offset1:30
	v_max3_f32 v4, v232, s22, v233
	v_max3_f32 v4, v4, v234, v235
	v_max3_f32 v4, v4, v236, v237
	v_max3_f32 v4, v4, v238, v239
	v_max3_f32 v4, v4, v240, v241
	v_max3_f32 v4, v4, v242, v243
	v_max3_f32 v4, v4, v244, v245
	v_max3_f32 v4, v4, v246, v247
	v_mfma_f32_32x32x16_bf16 v[48:63], v[180:183], v[68:71], v[48:63]
	v_mov_b32_e32 v5, v4
	s_nop 1
	v_permlane32_swap_b32_e32 v4, v5
	v_max_f32_e32 v4, v4, v5
	v_mul_f32_e32 v4, 0x3e38aa3b, v4
	v_max_f32_e32 v6, v147, v4
	v_sub_f32_e32 v0, v147, v6
	v_pk_fma_f32 v[232:233], v[232:233], s[22:23], v[6:7] op_sel:[0,1,0] op_sel_hi:[1,1,0] neg_lo:[0,0,1] neg_hi:[0,0,1]
	v_pk_fma_f32 v[234:235], v[234:235], s[22:23], v[6:7] op_sel:[0,1,0] op_sel_hi:[1,1,0] neg_lo:[0,0,1] neg_hi:[0,0,1]
	v_pk_fma_f32 v[236:237], v[236:237], s[22:23], v[6:7] op_sel:[0,1,0] op_sel_hi:[1,1,0] neg_lo:[0,0,1] neg_hi:[0,0,1]
	v_pk_fma_f32 v[238:239], v[238:239], s[22:23], v[6:7] op_sel:[0,1,0] op_sel_hi:[1,1,0] neg_lo:[0,0,1] neg_hi:[0,0,1]
	v_pk_fma_f32 v[240:241], v[240:241], s[22:23], v[6:7] op_sel:[0,1,0] op_sel_hi:[1,1,0] neg_lo:[0,0,1] neg_hi:[0,0,1]
	v_pk_fma_f32 v[242:243], v[242:243], s[22:23], v[6:7] op_sel:[0,1,0] op_sel_hi:[1,1,0] neg_lo:[0,0,1] neg_hi:[0,0,1]
	v_pk_fma_f32 v[244:245], v[244:245], s[22:23], v[6:7] op_sel:[0,1,0] op_sel_hi:[1,1,0] neg_lo:[0,0,1] neg_hi:[0,0,1]
	v_pk_fma_f32 v[246:247], v[246:247], s[22:23], v[6:7] op_sel:[0,1,0] op_sel_hi:[1,1,0] neg_lo:[0,0,1] neg_hi:[0,0,1]
	v_mfma_f32_32x32x16_bf16 v[48:63], v[184:187], v[72:75], v[48:63]
	v_exp_f32_e32 v0, v0
	v_exp_f32_e32 v232, v232
	v_exp_f32_e32 v233, v233
	v_exp_f32_e32 v234, v234
	v_exp_f32_e32 v235, v235
	v_exp_f32_e32 v236, v236
	v_exp_f32_e32 v237, v237
	v_exp_f32_e32 v238, v238
	v_mfma_f32_32x32x16_bf16 v[48:63], v[200:203], v[76:79], v[48:63]
	ds_read_b128 v[176:179], v248 offset:20480
	ds_read_b128 v[180:183], v249 offset:20480
	ds_read_b128 v[184:187], v250 offset:20480
	ds_read_b128 v[200:203], v251 offset:20480
	v_exp_f32_e32 v239, v239
	v_exp_f32_e32 v240, v240
	v_exp_f32_e32 v241, v241
	v_exp_f32_e32 v242, v242
	v_exp_f32_e32 v243, v243
	v_exp_f32_e32 v244, v244
	v_exp_f32_e32 v245, v245
	v_exp_f32_e32 v246, v246
	v_exp_f32_e32 v247, v247
	v_mov_b32_e32 v147, v6
	v_pk_add_f32 v[2:3], v[232:233], v[234:235]
	v_pk_add_f32 v[8:9], v[236:237], v[238:239]
	v_pk_add_f32 v[12:13], v[240:241], v[242:243]
	v_pk_add_f32 v[14:15], v[244:245], v[246:247]
	v_pk_add_f32 v[2:3], v[2:3], v[8:9]
	v_pk_add_f32 v[12:13], v[12:13], v[14:15]
	v_pk_add_f32 v[2:3], v[2:3], v[12:13]
	v_add_f32_e32 v10, v2, v3
	v_mov_b32_e32 v11, v10
	s_nop 1
	v_permlane32_swap_b32_e32 v10, v11
	v_cmp_neq_f32_e32 vcc, 1.0, v0
	s_cbranch_vccz .Lattn_pkeep_3
	v_pk_mul_f32 v[30:31], v[30:31], v[0:1] op_sel_hi:[1,0]
	v_pk_mul_f32 v[28:29], v[28:29], v[0:1] op_sel_hi:[1,0]
	v_pk_mul_f32 v[26:27], v[26:27], v[0:1] op_sel_hi:[1,0]
	v_pk_mul_f32 v[24:25], v[24:25], v[0:1] op_sel_hi:[1,0]
	v_pk_mul_f32 v[22:23], v[22:23], v[0:1] op_sel_hi:[1,0]
	v_pk_mul_f32 v[20:21], v[20:21], v[0:1] op_sel_hi:[1,0]
	v_pk_mul_f32 v[18:19], v[18:19], v[0:1] op_sel_hi:[1,0]
	v_pk_mul_f32 v[16:17], v[16:17], v[0:1] op_sel_hi:[1,0]
	v_pk_mul_f32 v[46:47], v[46:47], v[0:1] op_sel_hi:[1,0]
	v_pk_mul_f32 v[44:45], v[44:45], v[0:1] op_sel_hi:[1,0]
	v_pk_mul_f32 v[42:43], v[42:43], v[0:1] op_sel_hi:[1,0]
	v_pk_mul_f32 v[40:41], v[40:41], v[0:1] op_sel_hi:[1,0]
	v_pk_mul_f32 v[38:39], v[38:39], v[0:1] op_sel_hi:[1,0]
	v_pk_mul_f32 v[36:37], v[36:37], v[0:1] op_sel_hi:[1,0]
	v_pk_mul_f32 v[34:35], v[34:35], v[0:1] op_sel_hi:[1,0]
	v_pk_mul_f32 v[32:33], v[32:33], v[0:1] op_sel_hi:[1,0]
; DI unsigned pack2bf(float a, float b) { const f2_t v = {a, b}; return __builtin_bit_cast(unsigned, __builtin_convertvector(v, bf2_t)); }
; DI float xor32_max(float v) { const auto r = __builtin_amdgcn_permlane32_swap(__float_as_uint(v), __float_as_uint(v), false, false); return fmaxf(__uint_as_float(r[0]), __uint_as_float(r[1])); }
; DI void attn_task(const Params& P, int bh, int n, int t, int lane, const char* Ks, const char* Vs) {
;     ...
;     for (int s = 0; s < 4; ++s) {
;       const bf16x8 kf = *reinterpret_cast<const bf16x8*>(Ks + krow * 128 + (((2 * s + hh) ^ ((krow >> 1) & 7)) * 16));
;       S = __builtin_amdgcn_mfma_f32_32x32x16_bf16(kf, qf[s], S, 0, 0, 0);
;     }
;     const bool diag = own && (kt == t);
;     constexpr float SC2 = 0.125f * 1.4426950408889634f;
;     float mx = -1e30f;
; #pragma unroll
;     for (int i = 0; i < 16; ++i) {
;       if (diag && (kbase + crow(i, hh) > lq)) S[i] = -1e30f;
;       mx = fmaxf(mx, S[i]);
;     }
;     mx = xor32_max(mx);
;     const float m_new = fmaxf(m_run, mx * SC2);
;     const float alpha = __builtin_amdgcn_exp2f(m_run - m_new);
;     float rs = 0.f;
; #pragma unroll
;     for (int i = 0; i < 16; ++i) { float pv = __builtin_amdgcn_exp2f(fmaf(S[i], SC2, -m_new)); S[i] = pv; rs += pv; }
;     rs = xor32_sum(rs);
;     l_run = l_run * alpha + rs; m_run = m_new;
;     if (__ballot(alpha != 1.f)) {
; #pragma unroll
;       for (int i = 0; i < 16; ++i) { O0[i] *= alpha; O1[i] *= alpha; }
;     }
; #pragma unroll
;     for (int s = 0; s < 2; ++s) {
;       const uint4 ppk = make_uint4(pack2bf(S[8 * s], S[8 * s + 1]), pack2bf(S[8 * s + 2], S[8 * s + 3]), pack2bf(S[8 * s + 4], S[8 * s + 5]), pack2bf(S[8 * s + 6], S[8 * s + 7]));
;       const bf16x8 pf = __builtin_bit_cast(bf16x8, ppk);
; #pragma unroll
;       for (int dt = 0; dt < 2; ++dt) {
;         const char* vp = Vs + (dt * 32 + r) * 528 + (kt * 32 + 16 * s + 4 * hh) * 2;
;         const uint2 lo = *reinterpret_cast<const uint2*>(vp), hi = *reinterpret_cast<const uint2*>(vp + 16);
;         const uint4 vv = make_uint4(lo.x, lo.y, hi.x, hi.y);
;         if (dt == 0) O0 = __builtin_amdgcn_mfma_f32_32x32x16_bf16(__builtin_bit_cast(bf16x8, vv), pf, O0, 0, 0, 0);
;         else O1 = __builtin_amdgcn_mfma_f32_32x32x16_bf16(__builtin_bit_cast(bf16x8, vv), pf, O1, 0, 0, 0);
;       }
;     }
.Lattn_pkeep_3:
	v_add_f32_e32 v4, v10, v11
	v_fmac_f32_e32 v4, v155, v0
	v_cvt_pk_bf16_f32 v8, v232, v233
	v_cvt_pk_bf16_f32 v9, v234, v235
	v_cvt_pk_bf16_f32 v10, v236, v237
	v_cvt_pk_bf16_f32 v11, v238, v239
	v_cvt_pk_bf16_f32 v12, v240, v241
	v_cvt_pk_bf16_f32 v13, v242, v243
	v_cvt_pk_bf16_f32 v14, v244, v245
	v_cvt_pk_bf16_f32 v15, v246, v247
	v_mov_b32_e32 v155, v4
	s_waitcnt lgkmcnt(0)
	v_mfma_f32_32x32x16_bf16 v[16:31], v[216:219], v[8:11], v[16:31]
	v_mfma_f32_32x32x16_bf16 v[32:47], v[220:223], v[8:11], v[32:47]
	v_mfma_f32_32x32x16_bf16 v[16:31], v[224:227], v[12:15], v[16:31]
	v_mfma_f32_32x32x16_bf16 v[32:47], v[228:231], v[12:15], v[32:47]
	s_waitcnt lgkmcnt(0)
	v_mfma_f32_32x32x16_bf16 v[232:247], v[176:179], v[64:67], 0
	ds_read2_b64 v[216:219], v210 offset0:32 offset1:34
	ds_read2_b64 v[220:223], v211 offset0:32 offset1:34
	ds_read2_b64 v[224:227], v210 offset0:36 offset1:38
	ds_read2_b64 v[228:231], v211 offset0:36 offset1:38
	v_max3_f32 v4, v48, s22, v49
	v_max3_f32 v4, v4, v50, v51
	v_max3_f32 v4, v4, v52, v53
	v_max3_f32 v4, v4, v54, v55
	v_max3_f32 v4, v4, v56, v57
	v_max3_f32 v4, v4, v58, v59
	v_max3_f32 v4, v4, v60, v61
	v_max3_f32 v4, v4, v62, v63
	v_mfma_f32_32x32x16_bf16 v[232:247], v[180:183], v[68:71], v[232:247]
	v_mov_b32_e32 v5, v4
	s_nop 1
	v_permlane32_swap_b32_e32 v4, v5
	v_max_f32_e32 v4, v4, v5
	v_mul_f32_e32 v4, 0x3e38aa3b, v4
	v_max_f32_e32 v6, v147, v4
	v_sub_f32_e32 v0, v147, v6
	v_pk_fma_f32 v[48:49], v[48:49], s[22:23], v[6:7] op_sel:[0,1,0] op_sel_hi:[1,1,0] neg_lo:[0,0,1] neg_hi:[0,0,1]
	v_pk_fma_f32 v[50:51], v[50:51], s[22:23], v[6:7] op_sel:[0,1,0] op_sel_hi:[1,1,0] neg_lo:[0,0,1] neg_hi:[0,0,1]
	v_pk_fma_f32 v[52:53], v[52:53], s[22:23], v[6:7] op_sel:[0,1,0] op_sel_hi:[1,1,0] neg_lo:[0,0,1] neg_hi:[0,0,1]
	v_pk_fma_f32 v[54:55], v[54:55], s[22:23], v[6:7] op_sel:[0,1,0] op_sel_hi:[1,1,0] neg_lo:[0,0,1] neg_hi:[0,0,1]
	v_pk_fma_f32 v[56:57], v[56:57], s[22:23], v[6:7] op_sel:[0,1,0] op_sel_hi:[1,1,0] neg_lo:[0,0,1] neg_hi:[0,0,1]
	v_pk_fma_f32 v[58:59], v[58:59], s[22:23], v[6:7] op_sel:[0,1,0] op_sel_hi:[1,1,0] neg_lo:[0,0,1] neg_hi:[0,0,1]
	v_pk_fma_f32 v[60:61], v[60:61], s[22:23], v[6:7] op_sel:[0,1,0] op_sel_hi:[1,1,0] neg_lo:[0,0,1] neg_hi:[0,0,1]
	v_pk_fma_f32 v[62:63], v[62:63], s[22:23], v[6:7] op_sel:[0,1,0] op_sel_hi:[1,1,0] neg_lo:[0,0,1] neg_hi:[0,0,1]
	v_mfma_f32_32x32x16_bf16 v[232:247], v[184:187], v[72:75], v[232:247]
	v_exp_f32_e32 v0, v0
	v_exp_f32_e32 v48, v48
	v_exp_f32_e32 v49, v49
	v_exp_f32_e32 v50, v50
	v_exp_f32_e32 v51, v51
	v_exp_f32_e32 v52, v52
	v_exp_f32_e32 v53, v53
	v_exp_f32_e32 v54, v54
	v_mfma_f32_32x32x16_bf16 v[232:247], v[200:203], v[76:79], v[232:247]
	ds_read_b128 v[176:179], v248 offset:24576
	ds_read_b128 v[180:183], v249 offset:24576
	ds_read_b128 v[184:187], v250 offset:24576
	ds_read_b128 v[200:203], v251 offset:24576
	v_exp_f32_e32 v55, v55
	v_exp_f32_e32 v56, v56
	v_exp_f32_e32 v57, v57
	v_exp_f32_e32 v58, v58
	v_exp_f32_e32 v59, v59
	v_exp_f32_e32 v60, v60
	v_exp_f32_e32 v61, v61
	v_exp_f32_e32 v62, v62
	v_exp_f32_e32 v63, v63
	v_mov_b32_e32 v147, v6
	v_pk_add_f32 v[2:3], v[48:49], v[50:51]
	v_pk_add_f32 v[8:9], v[52:53], v[54:55]
	v_pk_add_f32 v[12:13], v[56:57], v[58:59]
	v_pk_add_f32 v[14:15], v[60:61], v[62:63]
	v_pk_add_f32 v[2:3], v[2:3], v[8:9]
	v_pk_add_f32 v[12:13], v[12:13], v[14:15]
	v_pk_add_f32 v[2:3], v[2:3], v[12:13]
	v_add_f32_e32 v10, v2, v3
	v_mov_b32_e32 v11, v10
	s_nop 1
	v_permlane32_swap_b32_e32 v10, v11
	v_cmp_neq_f32_e32 vcc, 1.0, v0
	s_cbranch_vccz .Lattn_pkeep_4
	v_pk_mul_f32 v[30:31], v[30:31], v[0:1] op_sel_hi:[1,0]
	v_pk_mul_f32 v[28:29], v[28:29], v[0:1] op_sel_hi:[1,0]
	v_pk_mul_f32 v[26:27], v[26:27], v[0:1] op_sel_hi:[1,0]
	v_pk_mul_f32 v[24:25], v[24:25], v[0:1] op_sel_hi:[1,0]
	v_pk_mul_f32 v[22:23], v[22:23], v[0:1] op_sel_hi:[1,0]
	v_pk_mul_f32 v[20:21], v[20:21], v[0:1] op_sel_hi:[1,0]
	v_pk_mul_f32 v[18:19], v[18:19], v[0:1] op_sel_hi:[1,0]
	v_pk_mul_f32 v[16:17], v[16:17], v[0:1] op_sel_hi:[1,0]
	v_pk_mul_f32 v[46:47], v[46:47], v[0:1] op_sel_hi:[1,0]
	v_pk_mul_f32 v[44:45], v[44:45], v[0:1] op_sel_hi:[1,0]
	v_pk_mul_f32 v[42:43], v[42:43], v[0:1] op_sel_hi:[1,0]
	v_pk_mul_f32 v[40:41], v[40:41], v[0:1] op_sel_hi:[1,0]
	v_pk_mul_f32 v[38:39], v[38:39], v[0:1] op_sel_hi:[1,0]
	v_pk_mul_f32 v[36:37], v[36:37], v[0:1] op_sel_hi:[1,0]
	v_pk_mul_f32 v[34:35], v[34:35], v[0:1] op_sel_hi:[1,0]
	v_pk_mul_f32 v[32:33], v[32:33], v[0:1] op_sel_hi:[1,0]
; DI unsigned pack2bf(float a, float b) { const f2_t v = {a, b}; return __builtin_bit_cast(unsigned, __builtin_convertvector(v, bf2_t)); }
; DI float xor32_max(float v) { const auto r = __builtin_amdgcn_permlane32_swap(__float_as_uint(v), __float_as_uint(v), false, false); return fmaxf(__uint_as_float(r[0]), __uint_as_float(r[1])); }
; DI void attn_task(const Params& P, int bh, int n, int t, int lane, const char* Ks, const char* Vs) {
;     ...
;     for (int s = 0; s < 4; ++s) {
;       const bf16x8 kf = *reinterpret_cast<const bf16x8*>(Ks + krow * 128 + (((2 * s + hh) ^ ((krow >> 1) & 7)) * 16));
;       S = __builtin_amdgcn_mfma_f32_32x32x16_bf16(kf, qf[s], S, 0, 0, 0);
;     }
;     const bool diag = own && (kt == t);
;     constexpr float SC2 = 0.125f * 1.4426950408889634f;
;     float mx = -1e30f;
; #pragma unroll
;     for (int i = 0; i < 16; ++i) {
;       if (diag && (kbase + crow(i, hh) > lq)) S[i] = -1e30f;
;       mx = fmaxf(mx, S[i]);
;     }
;     mx = xor32_max(mx);
;     const float m_new = fmaxf(m_run, mx * SC2);
;     const float alpha = __builtin_amdgcn_exp2f(m_run - m_new);
;     float rs = 0.f;
; #pragma unroll
;     for (int i = 0; i < 16; ++i) { float pv = __builtin_amdgcn_exp2f(fmaf(S[i], SC2, -m_new)); S[i] = pv; rs += pv; }
;     rs = xor32_sum(rs);
;     l_run = l_run * alpha + rs; m_run = m_new;
;     if (__ballot(alpha != 1.f)) {
; #pragma unroll
;       for (int i = 0; i < 16; ++i) { O0[i] *= alpha; O1[i] *= alpha; }
;     }
; #pragma unroll
;     for (int s = 0; s < 2; ++s) {
;       const uint4 ppk = make_uint4(pack2bf(S[8 * s], S[8 * s + 1]), pack2bf(S[8 * s + 2], S[8 * s + 3]), pack2bf(S[8 * s + 4], S[8 * s + 5]), pack2bf(S[8 * s + 6], S[8 * s + 7]));
;       const bf16x8 pf = __builtin_bit_cast(bf16x8, ppk);
; #pragma unroll
;       for (int dt = 0; dt < 2; ++dt) {
;         const char* vp = Vs + (dt * 32 + r) * 528 + (kt * 32 + 16 * s + 4 * hh) * 2;
;         const uint2 lo = *reinterpret_cast<const uint2*>(vp), hi = *reinterpret_cast<const uint2*>(vp + 16);
;         const uint4 vv = make_uint4(lo.x, lo.y, hi.x, hi.y);
;         if (dt == 0) O0 = __builtin_amdgcn_mfma_f32_32x32x16_bf16(__builtin_bit_cast(bf16x8, vv), pf, O0, 0, 0, 0);
;         else O1 = __builtin_amdgcn_mfma_f32_32x32x16_bf16(__builtin_bit_cast(bf16x8, vv), pf, O1, 0, 0, 0);
;       }
;     }
.Lattn_pkeep_4:
	v_add_f32_e32 v4, v10, v11
	v_fmac_f32_e32 v4, v155, v0
	v_cvt_pk_bf16_f32 v8, v48, v49
	v_cvt_pk_bf16_f32 v9, v50, v51
	v_cvt_pk_bf16_f32 v10, v52, v53
	v_cvt_pk_bf16_f32 v11, v54, v55
	v_cvt_pk_bf16_f32 v12, v56, v57
	v_cvt_pk_bf16_f32 v13, v58, v59
	v_cvt_pk_bf16_f32 v14, v60, v61
	v_cvt_pk_bf16_f32 v15, v62, v63
	v_mov_b32_e32 v155, v4
	s_waitcnt lgkmcnt(0)
	v_mfma_f32_32x32x16_bf16 v[16:31], v[216:219], v[8:11], v[16:31]
	v_mfma_f32_32x32x16_bf16 v[32:47], v[220:223], v[8:11], v[32:47]
	v_mfma_f32_32x32x16_bf16 v[16:31], v[224:227], v[12:15], v[16:31]
	v_mfma_f32_32x32x16_bf16 v[32:47], v[228:231], v[12:15], v[32:47]
	s_waitcnt lgkmcnt(0)
	v_mfma_f32_32x32x16_bf16 v[48:63], v[176:179], v[64:67], 0
	ds_read2_b64 v[216:219], v210 offset0:40 offset1:42
	ds_read2_b64 v[220:223], v211 offset0:40 offset1:42
	ds_read2_b64 v[224:227], v210 offset0:44 offset1:46
	ds_read2_b64 v[228:231], v211 offset0:44 offset1:46
	v_max3_f32 v4, v232, s22, v233
	v_max3_f32 v4, v4, v234, v235
	v_max3_f32 v4, v4, v236, v237
	v_max3_f32 v4, v4, v238, v239
	v_max3_f32 v4, v4, v240, v241
	v_max3_f32 v4, v4, v242, v243
	v_max3_f32 v4, v4, v244, v245
	v_max3_f32 v4, v4, v246, v247
	v_mfma_f32_32x32x16_bf16 v[48:63], v[180:183], v[68:71], v[48:63]
	v_mov_b32_e32 v5, v4
	s_nop 1
	v_permlane32_swap_b32_e32 v4, v5
	v_max_f32_e32 v4, v4, v5
	v_mul_f32_e32 v4, 0x3e38aa3b, v4
	v_max_f32_e32 v6, v147, v4
	v_sub_f32_e32 v0, v147, v6
	v_pk_fma_f32 v[232:233], v[232:233], s[22:23], v[6:7] op_sel:[0,1,0] op_sel_hi:[1,1,0] neg_lo:[0,0,1] neg_hi:[0,0,1]
	v_pk_fma_f32 v[234:235], v[234:235], s[22:23], v[6:7] op_sel:[0,1,0] op_sel_hi:[1,1,0] neg_lo:[0,0,1] neg_hi:[0,0,1]
	v_pk_fma_f32 v[236:237], v[236:237], s[22:23], v[6:7] op_sel:[0,1,0] op_sel_hi:[1,1,0] neg_lo:[0,0,1] neg_hi:[0,0,1]
	v_pk_fma_f32 v[238:239], v[238:239], s[22:23], v[6:7] op_sel:[0,1,0] op_sel_hi:[1,1,0] neg_lo:[0,0,1] neg_hi:[0,0,1]
	v_pk_fma_f32 v[240:241], v[240:241], s[22:23], v[6:7] op_sel:[0,1,0] op_sel_hi:[1,1,0] neg_lo:[0,0,1] neg_hi:[0,0,1]
	v_pk_fma_f32 v[242:243], v[242:243], s[22:23], v[6:7] op_sel:[0,1,0] op_sel_hi:[1,1,0] neg_lo:[0,0,1] neg_hi:[0,0,1]
	v_pk_fma_f32 v[244:245], v[244:245], s[22:23], v[6:7] op_sel:[0,1,0] op_sel_hi:[1,1,0] neg_lo:[0,0,1] neg_hi:[0,0,1]
	v_pk_fma_f32 v[246:247], v[246:247], s[22:23], v[6:7] op_sel:[0,1,0] op_sel_hi:[1,1,0] neg_lo:[0,0,1] neg_hi:[0,0,1]
	v_mfma_f32_32x32x16_bf16 v[48:63], v[184:187], v[72:75], v[48:63]
	v_exp_f32_e32 v0, v0
	v_exp_f32_e32 v232, v232
	v_exp_f32_e32 v233, v233
	v_exp_f32_e32 v234, v234
	v_exp_f32_e32 v235, v235
	v_exp_f32_e32 v236, v236
	v_exp_f32_e32 v237, v237
	v_exp_f32_e32 v238, v238
	v_mfma_f32_32x32x16_bf16 v[48:63], v[200:203], v[76:79], v[48:63]
	ds_read_b128 v[176:179], v248 offset:28672
	ds_read_b128 v[180:183], v249 offset:28672
	ds_read_b128 v[184:187], v250 offset:28672
	ds_read_b128 v[200:203], v251 offset:28672
	v_exp_f32_e32 v239, v239
	v_exp_f32_e32 v240, v240
	v_exp_f32_e32 v241, v241
	v_exp_f32_e32 v242, v242
	v_exp_f32_e32 v243, v243
	v_exp_f32_e32 v244, v244
	v_exp_f32_e32 v245, v245
	v_exp_f32_e32 v246, v246
	v_exp_f32_e32 v247, v247
	v_mov_b32_e32 v147, v6
	v_pk_add_f32 v[2:3], v[232:233], v[234:235]
	v_pk_add_f32 v[8:9], v[236:237], v[238:239]
	v_pk_add_f32 v[12:13], v[240:241], v[242:243]
	v_pk_add_f32 v[14:15], v[244:245], v[246:247]
	v_pk_add_f32 v[2:3], v[2:3], v[8:9]
	v_pk_add_f32 v[12:13], v[12:13], v[14:15]
	v_pk_add_f32 v[2:3], v[2:3], v[12:13]
	v_add_f32_e32 v10, v2, v3
	v_mov_b32_e32 v11, v10
	s_nop 1
	v_permlane32_swap_b32_e32 v10, v11
	v_cmp_neq_f32_e32 vcc, 1.0, v0
	s_cbranch_vccz .Lattn_pkeep_5
	v_pk_mul_f32 v[30:31], v[30:31], v[0:1] op_sel_hi:[1,0]
	v_pk_mul_f32 v[28:29], v[28:29], v[0:1] op_sel_hi:[1,0]
	v_pk_mul_f32 v[26:27], v[26:27], v[0:1] op_sel_hi:[1,0]
	v_pk_mul_f32 v[24:25], v[24:25], v[0:1] op_sel_hi:[1,0]
	v_pk_mul_f32 v[22:23], v[22:23], v[0:1] op_sel_hi:[1,0]
	v_pk_mul_f32 v[20:21], v[20:21], v[0:1] op_sel_hi:[1,0]
	v_pk_mul_f32 v[18:19], v[18:19], v[0:1] op_sel_hi:[1,0]
	v_pk_mul_f32 v[16:17], v[16:17], v[0:1] op_sel_hi:[1,0]
	v_pk_mul_f32 v[46:47], v[46:47], v[0:1] op_sel_hi:[1,0]
	v_pk_mul_f32 v[44:45], v[44:45], v[0:1] op_sel_hi:[1,0]
	v_pk_mul_f32 v[42:43], v[42:43], v[0:1] op_sel_hi:[1,0]
	v_pk_mul_f32 v[40:41], v[40:41], v[0:1] op_sel_hi:[1,0]
	v_pk_mul_f32 v[38:39], v[38:39], v[0:1] op_sel_hi:[1,0]
	v_pk_mul_f32 v[36:37], v[36:37], v[0:1] op_sel_hi:[1,0]
	v_pk_mul_f32 v[34:35], v[34:35], v[0:1] op_sel_hi:[1,0]
	v_pk_mul_f32 v[32:33], v[32:33], v[0:1] op_sel_hi:[1,0]
; DI unsigned pack2bf(float a, float b) { const f2_t v = {a, b}; return __builtin_bit_cast(unsigned, __builtin_convertvector(v, bf2_t)); }
; DI float xor32_max(float v) { const auto r = __builtin_amdgcn_permlane32_swap(__float_as_uint(v), __float_as_uint(v), false, false); return fmaxf(__uint_as_float(r[0]), __uint_as_float(r[1])); }
; DI void attn_task(const Params& P, int bh, int n, int t, int lane, const char* Ks, const char* Vs) {
;     ...
;     for (int s = 0; s < 4; ++s) {
;       const bf16x8 kf = *reinterpret_cast<const bf16x8*>(Ks + krow * 128 + (((2 * s + hh) ^ ((krow >> 1) & 7)) * 16));
;       S = __builtin_amdgcn_mfma_f32_32x32x16_bf16(kf, qf[s], S, 0, 0, 0);
;     }
;     const bool diag = own && (kt == t);
;     constexpr float SC2 = 0.125f * 1.4426950408889634f;
;     float mx = -1e30f;
; #pragma unroll
;     for (int i = 0; i < 16; ++i) {
;       if (diag && (kbase + crow(i, hh) > lq)) S[i] = -1e30f;
;       mx = fmaxf(mx, S[i]);
;     }
;     mx = xor32_max(mx);
;     const float m_new = fmaxf(m_run, mx * SC2);
;     const float alpha = __builtin_amdgcn_exp2f(m_run - m_new);
;     float rs = 0.f;
; #pragma unroll
;     for (int i = 0; i < 16; ++i) { float pv = __builtin_amdgcn_exp2f(fmaf(S[i], SC2, -m_new)); S[i] = pv; rs += pv; }
;     rs = xor32_sum(rs);
;     l_run = l_run * alpha + rs; m_run = m_new;
;     if (__ballot(alpha != 1.f)) {
; #pragma unroll
;       for (int i = 0; i < 16; ++i) { O0[i] *= alpha; O1[i] *= alpha; }
;     }
; #pragma unroll
;     for (int s = 0; s < 2; ++s) {
;       const uint4 ppk = make_uint4(pack2bf(S[8 * s], S[8 * s + 1]), pack2bf(S[8 * s + 2], S[8 * s + 3]), pack2bf(S[8 * s + 4], S[8 * s + 5]), pack2bf(S[8 * s + 6], S[8 * s + 7]));
;       const bf16x8 pf = __builtin_bit_cast(bf16x8, ppk);
; #pragma unroll
;       for (int dt = 0; dt < 2; ++dt) {
;         const char* vp = Vs + (dt * 32 + r) * 528 + (kt * 32 + 16 * s + 4 * hh) * 2;
;         const uint2 lo = *reinterpret_cast<const uint2*>(vp), hi = *reinterpret_cast<const uint2*>(vp + 16);
;         const uint4 vv = make_uint4(lo.x, lo.y, hi.x, hi.y);
;         if (dt == 0) O0 = __builtin_amdgcn_mfma_f32_32x32x16_bf16(__builtin_bit_cast(bf16x8, vv), pf, O0, 0, 0, 0);
;         else O1 = __builtin_amdgcn_mfma_f32_32x32x16_bf16(__builtin_bit_cast(bf16x8, vv), pf, O1, 0, 0, 0);
;       }
;     }
.Lattn_pkeep_5:
	v_add_f32_e32 v4, v10, v11
	v_fmac_f32_e32 v4, v155, v0
	v_cvt_pk_bf16_f32 v8, v232, v233
	v_cvt_pk_bf16_f32 v9, v234, v235
	v_cvt_pk_bf16_f32 v10, v236, v237
	v_cvt_pk_bf16_f32 v11, v238, v239
	v_cvt_pk_bf16_f32 v12, v240, v241
	v_cvt_pk_bf16_f32 v13, v242, v243
	v_cvt_pk_bf16_f32 v14, v244, v245
	v_cvt_pk_bf16_f32 v15, v246, v247
	v_mov_b32_e32 v155, v4
	s_waitcnt lgkmcnt(0)
	v_mfma_f32_32x32x16_bf16 v[16:31], v[216:219], v[8:11], v[16:31]
	v_mfma_f32_32x32x16_bf16 v[32:47], v[220:223], v[8:11], v[32:47]
	v_mfma_f32_32x32x16_bf16 v[16:31], v[224:227], v[12:15], v[16:31]
	v_mfma_f32_32x32x16_bf16 v[32:47], v[228:231], v[12:15], v[32:47]
	s_waitcnt lgkmcnt(0)
	v_mfma_f32_32x32x16_bf16 v[232:247], v[176:179], v[64:67], 0
	ds_read2_b64 v[216:219], v210 offset0:48 offset1:50
	ds_read2_b64 v[220:223], v211 offset0:48 offset1:50
	ds_read2_b64 v[224:227], v210 offset0:52 offset1:54
	ds_read2_b64 v[228:231], v211 offset0:52 offset1:54
	v_max3_f32 v4, v48, s22, v49
	v_max3_f32 v4, v4, v50, v51
	v_max3_f32 v4, v4, v52, v53
	v_max3_f32 v4, v4, v54, v55
	v_max3_f32 v4, v4, v56, v57
	v_max3_f32 v4, v4, v58, v59
	v_max3_f32 v4, v4, v60, v61
	v_max3_f32 v4, v4, v62, v63
	v_mfma_f32_32x32x16_bf16 v[232:247], v[180:183], v[68:71], v[232:247]
	v_mov_b32_e32 v5, v4
	s_nop 1
	v_permlane32_swap_b32_e32 v4, v5
	v_max_f32_e32 v4, v4, v5
	v_mul_f32_e32 v4, 0x3e38aa3b, v4
	v_max_f32_e32 v6, v147, v4
	v_sub_f32_e32 v0, v147, v6
	v_pk_fma_f32 v[48:49], v[48:49], s[22:23], v[6:7] op_sel:[0,1,0] op_sel_hi:[1,1,0] neg_lo:[0,0,1] neg_hi:[0,0,1]
	v_pk_fma_f32 v[50:51], v[50:51], s[22:23], v[6:7] op_sel:[0,1,0] op_sel_hi:[1,1,0] neg_lo:[0,0,1] neg_hi:[0,0,1]
	v_pk_fma_f32 v[52:53], v[52:53], s[22:23], v[6:7] op_sel:[0,1,0] op_sel_hi:[1,1,0] neg_lo:[0,0,1] neg_hi:[0,0,1]
	v_pk_fma_f32 v[54:55], v[54:55], s[22:23], v[6:7] op_sel:[0,1,0] op_sel_hi:[1,1,0] neg_lo:[0,0,1] neg_hi:[0,0,1]
	v_pk_fma_f32 v[56:57], v[56:57], s[22:23], v[6:7] op_sel:[0,1,0] op_sel_hi:[1,1,0] neg_lo:[0,0,1] neg_hi:[0,0,1]
	v_pk_fma_f32 v[58:59], v[58:59], s[22:23], v[6:7] op_sel:[0,1,0] op_sel_hi:[1,1,0] neg_lo:[0,0,1] neg_hi:[0,0,1]
	v_pk_fma_f32 v[60:61], v[60:61], s[22:23], v[6:7] op_sel:[0,1,0] op_sel_hi:[1,1,0] neg_lo:[0,0,1] neg_hi:[0,0,1]
	v_pk_fma_f32 v[62:63], v[62:63], s[22:23], v[6:7] op_sel:[0,1,0] op_sel_hi:[1,1,0] neg_lo:[0,0,1] neg_hi:[0,0,1]
	v_mfma_f32_32x32x16_bf16 v[232:247], v[184:187], v[72:75], v[232:247]
	v_exp_f32_e32 v0, v0
	v_exp_f32_e32 v48, v48
	v_exp_f32_e32 v49, v49
	v_exp_f32_e32 v50, v50
	v_exp_f32_e32 v51, v51
	v_exp_f32_e32 v52, v52
	v_exp_f32_e32 v53, v53
	v_exp_f32_e32 v54, v54
	v_mfma_f32_32x32x16_bf16 v[232:247], v[200:203], v[76:79], v[232:247]
	v_exp_f32_e32 v55, v55
	v_exp_f32_e32 v56, v56
	v_exp_f32_e32 v57, v57
	v_exp_f32_e32 v58, v58
	v_exp_f32_e32 v59, v59
	v_exp_f32_e32 v60, v60
	v_exp_f32_e32 v61, v61
	v_exp_f32_e32 v62, v62
	v_exp_f32_e32 v63, v63
	v_mov_b32_e32 v147, v6
	v_pk_add_f32 v[2:3], v[48:49], v[50:51]
	v_pk_add_f32 v[8:9], v[52:53], v[54:55]
	v_pk_add_f32 v[12:13], v[56:57], v[58:59]
	v_pk_add_f32 v[14:15], v[60:61], v[62:63]
	v_pk_add_f32 v[2:3], v[2:3], v[8:9]
	v_pk_add_f32 v[12:13], v[12:13], v[14:15]
	v_pk_add_f32 v[2:3], v[2:3], v[12:13]
	v_add_f32_e32 v10, v2, v3
	v_mov_b32_e32 v11, v10
	s_nop 1
	v_permlane32_swap_b32_e32 v10, v11
	v_cmp_neq_f32_e32 vcc, 1.0, v0
	s_cbranch_vccz .Lattn_pkeep_6
	v_pk_mul_f32 v[30:31], v[30:31], v[0:1] op_sel_hi:[1,0]
	v_pk_mul_f32 v[28:29], v[28:29], v[0:1] op_sel_hi:[1,0]
	v_pk_mul_f32 v[26:27], v[26:27], v[0:1] op_sel_hi:[1,0]
	v_pk_mul_f32 v[24:25], v[24:25], v[0:1] op_sel_hi:[1,0]
	v_pk_mul_f32 v[22:23], v[22:23], v[0:1] op_sel_hi:[1,0]
	v_pk_mul_f32 v[20:21], v[20:21], v[0:1] op_sel_hi:[1,0]
	v_pk_mul_f32 v[18:19], v[18:19], v[0:1] op_sel_hi:[1,0]
	v_pk_mul_f32 v[16:17], v[16:17], v[0:1] op_sel_hi:[1,0]
	v_pk_mul_f32 v[46:47], v[46:47], v[0:1] op_sel_hi:[1,0]
	v_pk_mul_f32 v[44:45], v[44:45], v[0:1] op_sel_hi:[1,0]
	v_pk_mul_f32 v[42:43], v[42:43], v[0:1] op_sel_hi:[1,0]
	v_pk_mul_f32 v[40:41], v[40:41], v[0:1] op_sel_hi:[1,0]
	v_pk_mul_f32 v[38:39], v[38:39], v[0:1] op_sel_hi:[1,0]
	v_pk_mul_f32 v[36:37], v[36:37], v[0:1] op_sel_hi:[1,0]
	v_pk_mul_f32 v[34:35], v[34:35], v[0:1] op_sel_hi:[1,0]
	v_pk_mul_f32 v[32:33], v[32:33], v[0:1] op_sel_hi:[1,0]
; DI unsigned pack2bf(float a, float b) { const f2_t v = {a, b}; return __builtin_bit_cast(unsigned, __builtin_convertvector(v, bf2_t)); }
; DI float xor32_max(float v) { const auto r = __builtin_amdgcn_permlane32_swap(__float_as_uint(v), __float_as_uint(v), false, false); return fmaxf(__uint_as_float(r[0]), __uint_as_float(r[1])); }
; DI void attn_task(const Params& P, int bh, int n, int t, int lane, const char* Ks, const char* Vs) {
;     ...
;     for (int s = 0; s < 4; ++s) {
;       const bf16x8 kf = *reinterpret_cast<const bf16x8*>(Ks + krow * 128 + (((2 * s + hh) ^ ((krow >> 1) & 7)) * 16));
;       S = __builtin_amdgcn_mfma_f32_32x32x16_bf16(kf, qf[s], S, 0, 0, 0);
;     }
;     const bool diag = own && (kt == t);
;     constexpr float SC2 = 0.125f * 1.4426950408889634f;
;     float mx = -1e30f;
; #pragma unroll
;     for (int i = 0; i < 16; ++i) {
;       if (diag && (kbase + crow(i, hh) > lq)) S[i] = -1e30f;
;       mx = fmaxf(mx, S[i]);
;     }
;     mx = xor32_max(mx);
;     const float m_new = fmaxf(m_run, mx * SC2);
;     const float alpha = __builtin_amdgcn_exp2f(m_run - m_new);
;     float rs = 0.f;
; #pragma unroll
;     for (int i = 0; i < 16; ++i) { float pv = __builtin_amdgcn_exp2f(fmaf(S[i], SC2, -m_new)); S[i] = pv; rs += pv; }
;     rs = xor32_sum(rs);
;     l_run = l_run * alpha + rs; m_run = m_new;
;     if (__ballot(alpha != 1.f)) {
; #pragma unroll
;       for (int i = 0; i < 16; ++i) { O0[i] *= alpha; O1[i] *= alpha; }
;     }
; #pragma unroll
;     for (int s = 0; s < 2; ++s) {
;       const uint4 ppk = make_uint4(pack2bf(S[8 * s], S[8 * s + 1]), pack2bf(S[8 * s + 2], S[8 * s + 3]), pack2bf(S[8 * s + 4], S[8 * s + 5]), pack2bf(S[8 * s + 6], S[8 * s + 7]));
;       const bf16x8 pf = __builtin_bit_cast(bf16x8, ppk);
; #pragma unroll
;       for (int dt = 0; dt < 2; ++dt) {
;         const char* vp = Vs + (dt * 32 + r) * 528 + (kt * 32 + 16 * s + 4 * hh) * 2;
;         const uint2 lo = *reinterpret_cast<const uint2*>(vp), hi = *reinterpret_cast<const uint2*>(vp + 16);
;         const uint4 vv = make_uint4(lo.x, lo.y, hi.x, hi.y);
;         if (dt == 0) O0 = __builtin_amdgcn_mfma_f32_32x32x16_bf16(__builtin_bit_cast(bf16x8, vv), pf, O0, 0, 0, 0);
;         else O1 = __builtin_amdgcn_mfma_f32_32x32x16_bf16(__builtin_bit_cast(bf16x8, vv), pf, O1, 0, 0, 0);
;       }
;     }
.Lattn_pkeep_6:
	v_add_f32_e32 v4, v10, v11
	v_fmac_f32_e32 v4, v155, v0
	v_cvt_pk_bf16_f32 v8, v48, v49
	v_cvt_pk_bf16_f32 v9, v50, v51
	v_cvt_pk_bf16_f32 v10, v52, v53
	v_cvt_pk_bf16_f32 v11, v54, v55
	v_cvt_pk_bf16_f32 v12, v56, v57
	v_cvt_pk_bf16_f32 v13, v58, v59
	v_cvt_pk_bf16_f32 v14, v60, v61
	v_cvt_pk_bf16_f32 v15, v62, v63
	v_mov_b32_e32 v155, v4
	s_waitcnt lgkmcnt(0)
	v_mfma_f32_32x32x16_bf16 v[16:31], v[216:219], v[8:11], v[16:31]
	v_mfma_f32_32x32x16_bf16 v[32:47], v[220:223], v[8:11], v[32:47]
	v_mfma_f32_32x32x16_bf16 v[16:31], v[224:227], v[12:15], v[16:31]
	v_mfma_f32_32x32x16_bf16 v[32:47], v[228:231], v[12:15], v[32:47]
	s_waitcnt lgkmcnt(0)
	v_max3_f32 v4, v232, s22, v233
	v_max3_f32 v4, v4, v234, v235
	v_max3_f32 v4, v4, v236, v237
	v_max3_f32 v4, v4, v238, v239
	v_max3_f32 v4, v4, v240, v241
	v_max3_f32 v4, v4, v242, v243
	v_max3_f32 v4, v4, v244, v245
	v_max3_f32 v4, v4, v246, v247
	ds_read2_b64 v[216:219], v210 offset0:56 offset1:58
	ds_read2_b64 v[220:223], v211 offset0:56 offset1:58
	ds_read2_b64 v[224:227], v210 offset0:60 offset1:62
	ds_read2_b64 v[228:231], v211 offset0:60 offset1:62
	v_mov_b32_e32 v5, v4
	s_nop 1
	v_permlane32_swap_b32_e32 v4, v5
	v_max_f32_e32 v4, v4, v5
	v_mul_f32_e32 v4, 0x3e38aa3b, v4
	v_max_f32_e32 v6, v147, v4
	v_sub_f32_e32 v0, v147, v6
	v_pk_fma_f32 v[232:233], v[232:233], s[22:23], v[6:7] op_sel:[0,1,0] op_sel_hi:[1,1,0] neg_lo:[0,0,1] neg_hi:[0,0,1]
	v_pk_fma_f32 v[234:235], v[234:235], s[22:23], v[6:7] op_sel:[0,1,0] op_sel_hi:[1,1,0] neg_lo:[0,0,1] neg_hi:[0,0,1]
	v_pk_fma_f32 v[236:237], v[236:237], s[22:23], v[6:7] op_sel:[0,1,0] op_sel_hi:[1,1,0] neg_lo:[0,0,1] neg_hi:[0,0,1]
	v_pk_fma_f32 v[238:239], v[238:239], s[22:23], v[6:7] op_sel:[0,1,0] op_sel_hi:[1,1,0] neg_lo:[0,0,1] neg_hi:[0,0,1]
	v_pk_fma_f32 v[240:241], v[240:241], s[22:23], v[6:7] op_sel:[0,1,0] op_sel_hi:[1,1,0] neg_lo:[0,0,1] neg_hi:[0,0,1]
	v_pk_fma_f32 v[242:243], v[242:243], s[22:23], v[6:7] op_sel:[0,1,0] op_sel_hi:[1,1,0] neg_lo:[0,0,1] neg_hi:[0,0,1]
	v_pk_fma_f32 v[244:245], v[244:245], s[22:23], v[6:7] op_sel:[0,1,0] op_sel_hi:[1,1,0] neg_lo:[0,0,1] neg_hi:[0,0,1]
	v_pk_fma_f32 v[246:247], v[246:247], s[22:23], v[6:7] op_sel:[0,1,0] op_sel_hi:[1,1,0] neg_lo:[0,0,1] neg_hi:[0,0,1]
	v_exp_f32_e32 v0, v0
	v_exp_f32_e32 v232, v232
	v_exp_f32_e32 v233, v233
	v_exp_f32_e32 v234, v234
	v_exp_f32_e32 v235, v235
	v_exp_f32_e32 v236, v236
	v_exp_f32_e32 v237, v237
	v_exp_f32_e32 v238, v238
	v_exp_f32_e32 v239, v239
	v_exp_f32_e32 v240, v240
	v_exp_f32_e32 v241, v241
	v_exp_f32_e32 v242, v242
	v_exp_f32_e32 v243, v243
	v_exp_f32_e32 v244, v244
	v_exp_f32_e32 v245, v245
	v_exp_f32_e32 v246, v246
	v_exp_f32_e32 v247, v247
	v_mov_b32_e32 v147, v6
	v_pk_add_f32 v[2:3], v[232:233], v[234:235]
	v_pk_add_f32 v[8:9], v[236:237], v[238:239]
	v_pk_add_f32 v[12:13], v[240:241], v[242:243]
	v_pk_add_f32 v[14:15], v[244:245], v[246:247]
	v_pk_add_f32 v[2:3], v[2:3], v[8:9]
	v_pk_add_f32 v[12:13], v[12:13], v[14:15]
	v_pk_add_f32 v[2:3], v[2:3], v[12:13]
	v_add_f32_e32 v10, v2, v3
	v_mov_b32_e32 v11, v10
	s_nop 1
	v_permlane32_swap_b32_e32 v10, v11
	v_cmp_neq_f32_e32 vcc, 1.0, v0
	s_cbranch_vccz .Lattn_pkeep_7
	v_pk_mul_f32 v[30:31], v[30:31], v[0:1] op_sel_hi:[1,0]
	v_pk_mul_f32 v[28:29], v[28:29], v[0:1] op_sel_hi:[1,0]
	v_pk_mul_f32 v[26:27], v[26:27], v[0:1] op_sel_hi:[1,0]
	v_pk_mul_f32 v[24:25], v[24:25], v[0:1] op_sel_hi:[1,0]
	v_pk_mul_f32 v[22:23], v[22:23], v[0:1] op_sel_hi:[1,0]
	v_pk_mul_f32 v[20:21], v[20:21], v[0:1] op_sel_hi:[1,0]
	v_pk_mul_f32 v[18:19], v[18:19], v[0:1] op_sel_hi:[1,0]
	v_pk_mul_f32 v[16:17], v[16:17], v[0:1] op_sel_hi:[1,0]
	v_pk_mul_f32 v[46:47], v[46:47], v[0:1] op_sel_hi:[1,0]
	v_pk_mul_f32 v[44:45], v[44:45], v[0:1] op_sel_hi:[1,0]
	v_pk_mul_f32 v[42:43], v[42:43], v[0:1] op_sel_hi:[1,0]
	v_pk_mul_f32 v[40:41], v[40:41], v[0:1] op_sel_hi:[1,0]
	v_pk_mul_f32 v[38:39], v[38:39], v[0:1] op_sel_hi:[1,0]
	v_pk_mul_f32 v[36:37], v[36:37], v[0:1] op_sel_hi:[1,0]
	v_pk_mul_f32 v[34:35], v[34:35], v[0:1] op_sel_hi:[1,0]
	v_pk_mul_f32 v[32:33], v[32:33], v[0:1] op_sel_hi:[1,0]
.Lattn_pkeep_7:
	v_add_f32_e32 v4, v10, v11
	v_fmac_f32_e32 v4, v155, v0
	v_cvt_pk_bf16_f32 v8, v232, v233
	v_cvt_pk_bf16_f32 v9, v234, v235
	v_cvt_pk_bf16_f32 v10, v236, v237
	v_cvt_pk_bf16_f32 v11, v238, v239
	v_cvt_pk_bf16_f32 v12, v240, v241
	v_cvt_pk_bf16_f32 v13, v242, v243
	v_cvt_pk_bf16_f32 v14, v244, v245
	v_cvt_pk_bf16_f32 v15, v246, v247
	v_mov_b32_e32 v155, v4
	s_waitcnt lgkmcnt(0)
	v_mfma_f32_32x32x16_bf16 v[16:31], v[216:219], v[8:11], v[16:31]
	v_mfma_f32_32x32x16_bf16 v[32:47], v[220:223], v[8:11], v[32:47]
	v_mfma_f32_32x32x16_bf16 v[16:31], v[224:227], v[12:15], v[16:31]
	v_mfma_f32_32x32x16_bf16 v[32:47], v[228:231], v[12:15], v[32:47]
